# neighbourhood attention: the 32 per-element bias lookups (one exec-masked LDS read + wait each) replaced by batched LDS reads and a select
# speedup vs baseline: 1.0095x; 1.0095x over previous
; #define LAS __attribute__((address_space(3)))
; #define MFMA32(a, b, c) __builtin_amdgcn_mfma_f32_32x32x16_bf16((a), (b), (c), 0, 0, 0)
; template <int MODE>
; __device__ __forceinline__ void attn_item(PK p, int l, LAS unsigned char* lds, int b, int h, int qb, bool ctxq, float lam, float lam_init) {
;     ...
;         bool active = true; int krow = 0;
;         if (nabias && t < nloc) { krow = loc0 + t; active = (krow >= sw) && (krow < sw + 8); }
;         bool slow = (MODE == 0) || (t == 0);
;         if (active) {
;           again:
;             LAS unsigned char* Kb = lds + cbuf * BUFSZ + koff;
;             f32x16 S[NCOMP][2];
; #pragma unroll
;             for (int c = 0; c < NCOMP; ++c)
; #pragma unroll
;                 for (int kt = 0; kt < 2; ++kt) {
;                     bf16x8 kf[NKS];
; #pragma unroll
;                     for (int ks = 0; ks < NKS; ++ks) kf[ks] = *(const LAS bf16x8*)(Kb + kt * 32 * KSTR + (c * NKS + ks) * 32);
; #pragma unroll
;                     for (int r = 0; r < 16; ++r) S[c][kt][r] = 0.f;
;                     __builtin_amdgcn_s_setprio(1);
; #pragma unroll
;                     for (int ks = 0; ks < NKS; ++ks) S[c][kt] = MFMA32(kf[ks], qf[c * NKS + ks], S[c][kt]);
;                     __builtin_amdgcn_s_setprio(0);
;                 }
.LBB0_144:
	s_cmp_ge_i32 s10, s6
	s_cselect_b64 s[0:1], -1, 0
	s_cmp_lt_i32 s10, s6
	s_mov_b32 s12, s94
	s_cselect_b64 s[94:95], -1, 0
	s_add_i32 s11, s65, s10
	v_cmp_ge_u32_e32 vcc, s11, v143
	v_cmp_lt_u32_e64 s[40:41], s11, v144
	s_and_b64 s[40:41], vcc, s[40:41]
	s_or_b64 s[62:63], s[0:1], s[40:41]
	s_and_saveexec_b64 s[40:41], s[62:63]
	s_cbranch_execz .LBB0_216
	s_mul_i32 s10, s88, 0x5400
	s_add_i32 s10, s10, 0
	v_add3_u32 v1, s10, v139, v108
	ds_read_b128 v[2:5], v1
	ds_read_b128 v[6:9], v1 offset:32
	ds_read_b128 v[10:13], v1 offset:64
	ds_read_b128 v[66:69], v1 offset:96
	s_setprio 1
	s_waitcnt lgkmcnt(3)
	v_mfma_f32_32x32x16_bf16 v[50:65], v[2:5], v[90:93], 0
	s_waitcnt lgkmcnt(2)
	v_mfma_f32_32x32x16_bf16 v[50:65], v[6:9], v[94:97], v[50:65]
	s_waitcnt lgkmcnt(1)
	v_mfma_f32_32x32x16_bf16 v[50:65], v[10:13], v[98:101], v[50:65]
	s_waitcnt lgkmcnt(0)
	v_mfma_f32_32x32x16_bf16 v[50:65], v[66:69], v[102:105], v[50:65]
	s_setprio 0
	ds_read_b128 v[2:5], v1 offset:4608
	ds_read_b128 v[6:9], v1 offset:4640
	ds_read_b128 v[10:13], v1 offset:4672
	ds_read_b128 v[120:123], v1 offset:4704
	s_setprio 1
	s_waitcnt lgkmcnt(3)
	v_mfma_f32_32x32x16_bf16 v[66:81], v[2:5], v[90:93], 0
	s_waitcnt lgkmcnt(2)
	v_mfma_f32_32x32x16_bf16 v[66:81], v[6:9], v[94:97], v[66:81]
	s_waitcnt lgkmcnt(1)
	v_mfma_f32_32x32x16_bf16 v[66:81], v[10:13], v[98:101], v[66:81]
	s_waitcnt lgkmcnt(0)
	v_mfma_f32_32x32x16_bf16 v[66:81], v[120:123], v[102:105], v[66:81]
	s_setprio 0
	s_mov_b64 s[62:63], -1
	s_andn2_b64 vcc, exec, s[94:95]
	s_nop 8
	v_mov_b32_e32 v137, v81
	v_mov_b32_e32 v136, v80
	v_mov_b32_e32 v135, v79
	v_mov_b32_e32 v134, v78
	v_mov_b32_e32 v133, v77
	v_mov_b32_e32 v132, v76
	v_mov_b32_e32 v131, v75
	v_mov_b32_e32 v130, v74
	v_mov_b32_e32 v129, v73
	v_mov_b32_e32 v128, v72
	v_mov_b32_e32 v127, v71
	v_mov_b32_e32 v126, v70
	v_mov_b32_e32 v125, v69
	v_mov_b32_e32 v124, v68
	v_mov_b32_e32 v123, v67
	v_mov_b32_e32 v122, v66
	v_mov_b32_e32 v121, v65
	v_mov_b32_e32 v120, v64
	v_mov_b32_e32 v15, v63
	v_mov_b32_e32 v14, v62
	v_mov_b32_e32 v13, v61
	v_mov_b32_e32 v12, v60
	v_mov_b32_e32 v11, v59
	v_mov_b32_e32 v10, v58
	v_mov_b32_e32 v9, v57
	v_mov_b32_e32 v8, v56
	v_mov_b32_e32 v7, v55
	v_mov_b32_e32 v6, v54
	v_mov_b32_e32 v5, v53
	v_mov_b32_e32 v4, v52
	v_mov_b32_e32 v3, v51
	v_mov_b32_e32 v2, v50
	s_cbranch_vccnz .LBB0_211
; #define LAS __attribute__((address_space(3)))
; template <int MODE>
; __device__ __forceinline__ void attn_item(PK p, int l, LAS unsigned char* lds, int b, int h, int qb, bool ctxq, float lam, float lam_init) {
;     ...
;                 if (nabias && t < nloc) {
;                     const LAS float* bt = (const LAS float*)(lds + BIAS_OFF) + (krow - rw + 7) * 31;
; #pragma unroll
;                     for (int kt = 0; kt < 2; ++kt)
; #pragma unroll
;                         for (int r = 0; r < 16; ++r) { const int jk = 32 * kt + (r & 3) + 8 * (r >> 2) + 4 * g; const bool ok = (jk >= cst) && (jk < cst + 16);
;                             const float bv = bt[clampi(jk - jq + 15, 0, 30)]; const float xv = ok ? (S[c][kt][r] + bv) : -1e30f; S[c][kt][r] = xv; mx = fmaxf(mx, xv); }
;                 } else {
; #pragma unroll
;                     for (int kt = 0; kt < 2; ++kt)
; #pragma unroll
;                         for (int r = 0; r < 16; r += 2) mx = fmaxf(fmaxf(mx, S[c][kt][r]), S[c][kt][r + 1]);
;                 }
;                 mxc[c] = mx;
	s_and_b64 s[0:1], s[0:1], exec
	s_cselect_b32 s0, 0, s11
	v_sub_u32_e32 v1, s0, v142
	s_movk_i32 s0, 0x7c
	v_mul_lo_u32 v1, v1, s0
	v_add_u32_e32 v1, 0, v1
	v_mov_b32_e32 v3, 0xf149f2ca
	v_mov_b32_e32 v2, 0xf149f2ca
	v_mov_b32_e32 v218, 0xf149f2ca
	v_lshl_add_u32 v2, v145, 2, v1
	v_lshl_add_u32 v3, v146, 2, v1
	v_lshl_add_u32 v4, v147, 2, v1
	v_lshl_add_u32 v5, v148, 2, v1
	v_lshl_add_u32 v6, v149, 2, v1
	v_lshl_add_u32 v7, v150, 2, v1
	v_lshl_add_u32 v8, v151, 2, v1
	v_lshl_add_u32 v9, v152, 2, v1
	v_lshl_add_u32 v10, v153, 2, v1
	v_lshl_add_u32 v11, v154, 2, v1
	v_lshl_add_u32 v12, v155, 2, v1
	v_lshl_add_u32 v13, v156, 2, v1
	v_lshl_add_u32 v14, v157, 2, v1
	v_lshl_add_u32 v15, v158, 2, v1
	v_lshl_add_u32 v120, v159, 2, v1
	v_lshl_add_u32 v121, v160, 2, v1
	v_lshl_add_u32 v122, v161, 2, v1
	v_lshl_add_u32 v123, v162, 2, v1
	v_lshl_add_u32 v124, v163, 2, v1
	v_lshl_add_u32 v125, v164, 2, v1
	v_lshl_add_u32 v126, v165, 2, v1
	v_lshl_add_u32 v127, v166, 2, v1
	v_lshl_add_u32 v128, v167, 2, v1
	v_lshl_add_u32 v129, v168, 2, v1
	v_lshl_add_u32 v130, v169, 2, v1
	v_lshl_add_u32 v131, v170, 2, v1
	v_lshl_add_u32 v132, v171, 2, v1
	v_lshl_add_u32 v133, v172, 2, v1
	v_lshl_add_u32 v134, v173, 2, v1
	v_lshl_add_u32 v135, v174, 2, v1
	v_lshl_add_u32 v136, v175, 2, v1
	v_lshl_add_u32 v137, v176, 2, v1
	ds_read_b32 v2, v2 offset:65440
	ds_read_b32 v3, v3 offset:65380
	ds_read_b32 v4, v4 offset:65380
	ds_read_b32 v5, v5 offset:65380
	ds_read_b32 v6, v6 offset:65380
	ds_read_b32 v7, v7 offset:65380
	ds_read_b32 v8, v8 offset:65380
	ds_read_b32 v9, v9 offset:65380
	ds_read_b32 v10, v10 offset:65380
	ds_read_b32 v11, v11 offset:65380
	ds_read_b32 v12, v12 offset:65380
	ds_read_b32 v13, v13 offset:65380
	s_waitcnt lgkmcnt(0)
	ds_read_b32 v14, v14 offset:65380
	ds_read_b32 v15, v15 offset:65380
	ds_read_b32 v120, v120 offset:65380
	ds_read_b32 v121, v121 offset:65380
	ds_read_b32 v122, v122 offset:65380
	ds_read_b32 v123, v123 offset:65380
	ds_read_b32 v124, v124 offset:65380
	ds_read_b32 v125, v125 offset:65380
	ds_read_b32 v126, v126 offset:65380
	ds_read_b32 v127, v127 offset:65380
	ds_read_b32 v128, v128 offset:65380
	ds_read_b32 v129, v129 offset:65380
	v_add_f32_e32 v2, v50, v2
	v_add_f32_e32 v3, v51, v3
	v_add_f32_e32 v4, v52, v4
	v_add_f32_e32 v5, v53, v5
	v_add_f32_e32 v6, v54, v6
	v_add_f32_e32 v7, v55, v7
	v_add_f32_e32 v8, v56, v8
	v_add_f32_e32 v9, v57, v9
	v_add_f32_e32 v10, v58, v10
	v_add_f32_e32 v11, v59, v11
	v_add_f32_e32 v12, v60, v12
	v_add_f32_e32 v13, v61, v13
	v_readlane_b32 s62, v255, 31
	v_readlane_b32 s63, v255, 32
	s_nop 1
	v_cndmask_b32_e64 v2, v218, v2, s[62:63]
	v_readlane_b32 s62, v255, 33
	v_readlane_b32 s63, v255, 34
	s_nop 1
	v_cndmask_b32_e64 v3, v218, v3, s[62:63]
	v_readlane_b32 s62, v255, 35
	v_readlane_b32 s63, v255, 36
	s_nop 1
	v_cndmask_b32_e64 v4, v218, v4, s[62:63]
	v_readlane_b32 s62, v255, 37
	v_readlane_b32 s63, v255, 38
	s_nop 1
	v_cndmask_b32_e64 v5, v218, v5, s[62:63]
	v_readlane_b32 s62, v255, 39
	v_readlane_b32 s63, v255, 40
	s_nop 1
	v_cndmask_b32_e64 v6, v218, v6, s[62:63]
	v_cndmask_b32_e64 v7, v218, v7, s[14:15]
	v_cndmask_b32_e64 v8, v218, v8, s[16:17]
	v_cndmask_b32_e64 v9, v218, v9, s[18:19]
	v_cndmask_b32_e64 v10, v218, v10, s[66:67]
	v_cndmask_b32_e64 v11, v218, v11, s[68:69]
	v_cndmask_b32_e64 v12, v218, v12, s[70:71]
	v_cndmask_b32_e64 v13, v218, v13, s[72:73]
	s_waitcnt lgkmcnt(0)
	ds_read_b32 v130, v130 offset:65380
	ds_read_b32 v131, v131 offset:65380
	ds_read_b32 v132, v132 offset:65380
	ds_read_b32 v133, v133 offset:65380
	ds_read_b32 v134, v134 offset:65380
	ds_read_b32 v135, v135 offset:65380
	ds_read_b32 v136, v136 offset:65380
	ds_read_b32 v137, v137 offset:65380
	v_add_f32_e32 v14, v62, v14
	v_add_f32_e32 v15, v63, v15
	v_add_f32_e32 v120, v64, v120
	v_add_f32_e32 v121, v65, v121
	v_add_f32_e32 v122, v66, v122
	v_add_f32_e32 v123, v67, v123
	v_add_f32_e32 v124, v68, v124
	v_add_f32_e32 v125, v69, v125
	v_add_f32_e32 v126, v70, v126
	v_add_f32_e32 v127, v71, v127
	v_add_f32_e32 v128, v72, v128
	v_add_f32_e32 v129, v73, v129
	v_cndmask_b32_e64 v14, v218, v14, s[74:75]
	v_cndmask_b32_e64 v15, v218, v15, s[76:77]
	v_cndmask_b32_e64 v120, v218, v120, s[78:79]
	v_cndmask_b32_e64 v121, v218, v121, s[80:81]
	v_cndmask_b32_e64 v122, v218, v122, s[58:59]
	v_cndmask_b32_e64 v123, v218, v123, s[42:43]
	v_cndmask_b32_e64 v124, v218, v124, s[60:61]
	v_cndmask_b32_e64 v125, v218, v125, s[2:3]
	v_cndmask_b32_e64 v126, v218, v126, s[84:85]
	v_cndmask_b32_e64 v127, v218, v127, s[38:39]
	v_cndmask_b32_e64 v128, v218, v128, s[46:47]
	v_cndmask_b32_e64 v129, v218, v129, s[48:49]
	s_waitcnt lgkmcnt(0)
	v_add_f32_e32 v130, v74, v130
	v_add_f32_e32 v131, v75, v131
	v_add_f32_e32 v132, v76, v132
	v_add_f32_e32 v133, v77, v133
	v_add_f32_e32 v134, v78, v134
	v_add_f32_e32 v135, v79, v135
	v_add_f32_e32 v136, v80, v136
	v_add_f32_e32 v137, v81, v137
	v_cndmask_b32_e64 v130, v218, v130, s[20:21]
	v_cndmask_b32_e64 v131, v218, v131, s[22:23]
	v_cndmask_b32_e64 v132, v218, v132, s[24:25]
	v_cndmask_b32_e64 v133, v218, v133, s[26:27]
	v_cndmask_b32_e64 v134, v218, v134, s[28:29]
	v_cndmask_b32_e64 v135, v218, v135, s[30:31]
	v_cndmask_b32_e64 v136, v218, v136, s[34:35]
	v_cndmask_b32_e64 v137, v218, v137, s[36:37]
	v_max3_f32 v1, v2, s33, v3
	v_max3_f32 v1, v1, v4, v5
	v_max3_f32 v1, v1, v6, v7
	v_max3_f32 v1, v1, v8, v9
	v_max3_f32 v1, v1, v10, v11
	v_max3_f32 v1, v1, v12, v13
	v_max3_f32 v1, v1, v14, v15
	v_max3_f32 v1, v1, v120, v121
	v_max3_f32 v1, v1, v122, v123
	v_max3_f32 v1, v1, v124, v125
	v_max3_f32 v1, v1, v126, v127
	v_max3_f32 v1, v1, v128, v129
	v_max3_f32 v1, v1, v130, v131
	v_max3_f32 v1, v1, v132, v133
	v_max3_f32 v1, v1, v134, v135
	v_max3_f32 v1, v1, v136, v137
	s_mov_b64 s[62:63], 0
